# speedup vs baseline: 1.0206x; 1.0046x over previous
.LBB0_187:
	s_or_b64 exec, exec, s[10:11]
	s_lshl_b32 s34, s18, 6
	s_lshl_b32 s3, s3, 24
	s_add_u32 s10, s37, s3
	s_addc_u32 s11, s91, 0
	s_add_u32 s3, s46, s3
	s_addc_u32 s18, s73, 0
	s_lshl_b32 s19, s34, 1
	s_add_u32 s40, s10, s19
	s_addc_u32 s41, s11, 0
	s_waitcnt vmcnt(0)
	v_cndmask_b32_e64 v1, 0, 1, s[8:9]
	s_add_u32 s42, s3, s19
	v_cmp_ne_u32_e32 vcc, 0, v1
	v_cndmask_b32_e64 v1, 0, 1, s[6:7]
	s_addc_u32 s43, s18, 0
	s_bcnt1_i32_b64 s3, vcc
	v_cmp_ne_u32_e32 vcc, 0, v1
	s_bcnt1_i32_b64 s6, vcc
	s_add_i32 s6, s6, s3
	s_and_b32 s3, s6, 0xfe
	s_add_i32 s10, s77, -4
	s_min_u32 s3, s3, s10
	v_ashrrev_i32_e32 v158, 3, v143
	s_lshl_b32 s78, s3, 6
	v_lshlrev_b32_e32 v33, 3, v143
	v_add_u32_e32 v2, s78, v158
	s_add_i32 s6, s78, 64
	v_and_b32_e32 v159, 56, v33
	v_ashrrev_i32_e32 v3, 31, v2
	v_add_u32_e32 v10, s6, v158
	v_lshlrev_b64 v[2:3], 11, v[2:3]
	v_lshlrev_b32_e32 v1, 1, v159
	v_ashrrev_i32_e32 v11, 31, v10
	v_or_b32_e32 v14, s6, v144
	v_or_b32_e32 v2, v2, v1
	v_lshlrev_b64 v[10:11], 11, v[10:11]
	v_ashrrev_i32_e32 v15, 31, v14
	v_lshl_add_u64 v[4:5], s[42:43], 0, v[2:3]
	v_lshl_add_u64 v[6:7], s[40:41], 0, v[2:3]
	v_or_b32_e32 v10, v10, v1
	v_lshl_add_u64 v[14:15], v[14:15], 2, s[38:39]
	global_load_dwordx4 v[2:5], v[4:5], off
	s_nop 0
	global_load_dwordx4 v[6:9], v[6:7], off
	v_lshl_add_u64 v[12:13], s[42:43], 0, v[10:11]
	v_lshl_add_u64 v[10:11], s[40:41], 0, v[10:11]
	global_load_dword v160, v[14:15], off
	global_load_dwordx4 v[112:115], v[12:13], off
	global_load_dwordx4 v[116:119], v[10:11], off
	v_lshlrev_b32_e32 v10, 8, v143
	v_lshlrev_b32_e32 v11, 6, v158
	v_lshlrev_b32_e32 v12, 4, v158
	v_and_b32_e32 v13, 8, v33
	s_mov_b32 s8, 0x7ffff800
	v_and_b32_e32 v10, 0x600, v10
	v_and_b32_e32 v15, 0x1f0, v12
	v_lshrrev_b32_e32 v251, 1, v15
	v_xor_b32_e32 v251, v251, v15
	v_and_b32_e32 v251, 64, v251
	v_lshl_or_b32 v251, v251, 1, v251
	v_xor_b32_e32 v15, v15, v251
	v_and_or_b32 v11, v11, s8, v13
	v_lshlrev_b32_e32 v14, 7, v158
	v_lshlrev_b32_e32 v12, 3, v158
	v_and_b32_e32 v12, 0x70, v12
	v_or3_b32 v10, v11, v15, v10
	v_cmp_gt_i32_e64 s[6:7], 64, v143
	v_bitop3_b32 v161, v1, v14, v12 bitop3:0xde
	v_lshlrev_b32_e32 v162, 1, v10
	v_cmp_lt_i32_e32 vcc, 63, v143
	s_waitcnt vmcnt(4)
	ds_write_b128 v162, v[2:5]
	s_waitcnt vmcnt(3)
	ds_write_b128 v161, v[6:9] offset:24576
	s_and_saveexec_b64 s[8:9], vcc
	s_xor_b64 s[8:9], exec, s[8:9]
	s_cbranch_execz .LBB0_189
	s_waitcnt vmcnt(1)
	ds_write_b128 v162, v[112:115] offset:8192
	s_waitcnt vmcnt(0)
	ds_write_b128 v161, v[116:119] offset:32768

.LBB0_197:
	s_mov_b32 s79, s10
	s_lshl_b32 s3, s86, 13
	s_mul_i32 s10, s86, 0xffffe100
	s_add_i32 s10, s3, s10
	v_or_b32_e32 v36, s3, v156
	v_lshl_or_b32 v44, v157, 2, s10
	v_or_b32_e32 v238, s3, v155
	v_or_b32_e32 v239, s3, v154
	v_or_b32_e32 v240, s3, v153
	ds_read_b128 v[206:209], v36 offset:24576
	ds_read_b128 v[48:51], v44 offset:51200
	ds_read_b128 v[52:55], v44 offset:51232
	ds_read_b128 v[56:59], v44 offset:51264
	ds_read_b128 v[60:63], v44 offset:51296
	ds_read_b128 v[210:213], v36 offset:28672
	ds_read_b128 v[32:35], v44 offset:51328
	ds_read_b128 v[36:39], v44 offset:51360
	ds_read_b128 v[40:43], v44 offset:51392
	ds_read_b128 v[44:47], v44 offset:51424
	ds_read_b128 v[214:217], v238 offset:24576
	ds_read_b128 v[218:221], v238 offset:28672
	ds_read_b128 v[222:225], v239 offset:24576
	ds_read_b128 v[226:229], v239 offset:28672
	ds_read_b128 v[230:233], v240 offset:24576
	s_add_i32 s81, s18, s19
	s_add_i32 s10, s81, 2
	v_add_u32_e32 v192, s78, v128
	v_add_f32_e32 v64, 0, v188
	v_add_f32_e32 v64, v190, v64
	v_add_f32_e32 v64, v186, v64
	v_add_f32_e32 v64, v189, v64
	v_add_f32_e32 v64, v184, v64
	v_add_f32_e32 v64, v187, v64
	v_add_f32_e32 v64, v183, v64
	v_add_f32_e32 v64, v185, v64
	v_add_f32_e32 v64, v171, v64
	s_waitcnt lgkmcnt(10)
	v_mfma_f32_32x32x16_bf16 v[48:63], v[206:209], v[96:99], v[48:63]
	v_add_f32_e32 v64, v180, v64
	v_add_f32_e32 v64, v170, v64
	v_add_f32_e32 v64, v172, v64
	v_exp_f32_e32 v72, v140
	v_add_f32_e32 v64, v169, v64
	v_exp_f32_e32 v73, v141
	v_add_f32_e32 v64, v182, v64
	v_exp_f32_e32 v74, v138
	v_add_f32_e32 v64, v173, v64
	ds_read_b128 v[234:237], v240 offset:28672
	s_waitcnt lgkmcnt(6)
	v_mfma_f32_32x32x16_bf16 v[32:47], v[210:213], v[96:99], v[32:47]
	v_exp_f32_e32 v75, v139
	v_add_f32_e32 v64, v181, v64
	v_exp_f32_e32 v76, v136
	v_add_f32_e32 v64, v72, v64
	v_exp_f32_e32 v77, v137
	v_add_f32_e32 v64, v73, v64
	v_exp_f32_e32 v78, v134
	v_add_f32_e32 v64, v74, v64
	v_exp_f32_e32 v79, v135
	s_waitcnt lgkmcnt(5)
	v_mfma_f32_32x32x16_bf16 v[48:63], v[214:217], v[100:103], v[48:63]
	v_add_f32_e32 v64, v75, v64
	v_exp_f32_e32 v80, v94
	v_add_f32_e32 v64, v76, v64
	v_exp_f32_e32 v81, v95
	v_add_f32_e32 v64, v77, v64
	v_exp_f32_e32 v82, v90
	v_add_f32_e32 v64, v78, v64
	v_exp_f32_e32 v83, v91
	v_add_f32_e32 v64, v79, v64
	s_waitcnt lgkmcnt(4)
	v_mfma_f32_32x32x16_bf16 v[32:47], v[218:221], v[100:103], v[32:47]
	v_exp_f32_e32 v84, v88
	v_add_f32_e32 v64, v80, v64
	v_exp_f32_e32 v85, v89
	v_add_f32_e32 v64, v81, v64
	v_exp_f32_e32 v86, v86
	v_add_f32_e32 v64, v82, v64
	v_exp_f32_e32 v87, v87
	v_add_f32_e32 v64, v83, v64
	v_add_f32_e32 v64, v84, v64
	s_waitcnt lgkmcnt(3)
	v_mfma_f32_32x32x16_bf16 v[48:63], v[222:225], v[104:107], v[48:63]
	v_add_f32_e32 v64, v85, v64
	v_add_f32_e32 v64, v86, v64
	v_add_f32_e32 v167, v87, v64
	v_mov_b32_e32 v168, v167
	v_cvt_pk_bf16_f32 v64, v188, v190
	v_cvt_pk_bf16_f32 v65, v186, v189
	v_cvt_pk_bf16_f32 v66, v184, v187
	v_cvt_pk_bf16_f32 v67, v183, v185
	v_cvt_pk_bf16_f32 v68, v171, v180
	s_waitcnt lgkmcnt(2)
	v_mfma_f32_32x32x16_bf16 v[32:47], v[226:229], v[104:107], v[32:47]
	v_cvt_pk_bf16_f32 v69, v170, v172
	v_cvt_pk_bf16_f32 v70, v169, v182
	v_cvt_pk_bf16_f32 v71, v173, v181
	v_cvt_pk_bf16_f32 v72, v72, v73
	v_cvt_pk_bf16_f32 v73, v74, v75
	v_cvt_pk_bf16_f32 v74, v76, v77
	v_cvt_pk_bf16_f32 v75, v78, v79
	v_cvt_pk_bf16_f32 v76, v80, v81
	v_cvt_pk_bf16_f32 v77, v82, v83
	s_waitcnt lgkmcnt(1)
	v_mfma_f32_32x32x16_bf16 v[48:63], v[230:233], v[108:111], v[48:63]
	v_cvt_pk_bf16_f32 v78, v84, v85
	v_cvt_pk_bf16_f32 v79, v86, v87
	s_nop 1
	v_permlane32_swap_b32_e32 v167, v168
	s_waitcnt lgkmcnt(0)
	v_mfma_f32_32x32x16_bf16 v[32:47], v[234:237], v[108:111], v[32:47]
	s_cmp_lt_i32 s10, 0
	s_cbranch_scc1 .LBB0_199
	v_add_u32_e32 v242, 0x60, v192
	v_add_u32_e32 v241, 64, v192
	v_cmp_le_i32_e32 vcc, v242, v152
	s_nop 7
	v_cndmask_b32_e32 v32, v176, v32, vcc
	v_cmp_lt_i32_e32 vcc, v241, v152
	s_nop 1
	v_cndmask_b32_e32 v49, v176, v49, vcc
	v_cmp_le_i32_e32 vcc, v241, v152
	v_add_u32_e32 v241, 0x61, v192
	s_nop 0
	v_cndmask_b32_e32 v48, v176, v48, vcc
	v_cmp_le_i32_e32 vcc, v241, v152
	v_add_u32_e32 v241, 0x42, v192
	s_nop 0
	v_cndmask_b32_e32 v33, v176, v33, vcc
	v_cmp_le_i32_e32 vcc, v241, v152
	v_add_u32_e32 v241, 0x62, v192
	s_nop 0
	v_cndmask_b32_e32 v50, v176, v50, vcc
	v_cmp_le_i32_e32 vcc, v241, v152
	v_add_u32_e32 v241, 0x43, v192
	s_nop 0
	v_cndmask_b32_e32 v34, v176, v34, vcc
	v_cmp_le_i32_e32 vcc, v241, v152
	v_add_u32_e32 v241, 0x63, v192
	s_nop 0
	v_cndmask_b32_e32 v51, v176, v51, vcc
	v_cmp_le_i32_e32 vcc, v241, v152
	v_add_u32_e32 v241, 0x48, v192
	s_nop 0
	v_cndmask_b32_e32 v35, v176, v35, vcc
	v_cmp_le_i32_e32 vcc, v241, v152
	v_add_u32_e32 v241, 0x68, v192
	s_nop 0
	v_cndmask_b32_e32 v52, v176, v52, vcc
	v_cmp_le_i32_e32 vcc, v241, v152
	v_add_u32_e32 v241, 0x49, v192
	s_nop 0
	v_cndmask_b32_e32 v36, v176, v36, vcc
	v_cmp_le_i32_e32 vcc, v241, v152
	v_add_u32_e32 v241, 0x69, v192
	s_nop 0
	v_cndmask_b32_e32 v53, v176, v53, vcc
	v_cmp_le_i32_e32 vcc, v241, v152
	v_add_u32_e32 v241, 0x4a, v192
	s_nop 0
	v_cndmask_b32_e32 v37, v176, v37, vcc
	v_cmp_le_i32_e32 vcc, v241, v152
	v_add_u32_e32 v241, 0x6a, v192
	s_nop 0
	v_cndmask_b32_e32 v54, v176, v54, vcc
	v_cmp_le_i32_e32 vcc, v241, v152
	v_add_u32_e32 v241, 0x4b, v192
	s_nop 0
	v_cndmask_b32_e32 v38, v176, v38, vcc
	v_cmp_le_i32_e32 vcc, v241, v152
	v_add_u32_e32 v241, 0x6b, v192
	s_nop 0
	v_cndmask_b32_e32 v55, v176, v55, vcc
	v_cmp_le_i32_e32 vcc, v241, v152
	v_add_u32_e32 v241, 0x50, v192
	s_nop 0
	v_cndmask_b32_e32 v39, v176, v39, vcc
	v_cmp_le_i32_e32 vcc, v241, v152
	v_add_u32_e32 v241, 0x70, v192
	s_nop 0
	v_cndmask_b32_e32 v56, v176, v56, vcc
	v_cmp_le_i32_e32 vcc, v241, v152
	v_add_u32_e32 v241, 0x51, v192
	s_nop 0
	v_cndmask_b32_e32 v40, v176, v40, vcc
	v_cmp_le_i32_e32 vcc, v241, v152
	v_add_u32_e32 v241, 0x71, v192
	s_nop 0
	v_cndmask_b32_e32 v57, v176, v57, vcc
	v_cmp_le_i32_e32 vcc, v241, v152
	v_add_u32_e32 v241, 0x52, v192
	s_nop 0
	v_cndmask_b32_e32 v41, v176, v41, vcc
	v_cmp_le_i32_e32 vcc, v241, v152
	v_add_u32_e32 v241, 0x72, v192
	s_nop 0
	v_cndmask_b32_e32 v58, v176, v58, vcc
	v_cmp_le_i32_e32 vcc, v241, v152
	v_add_u32_e32 v241, 0x53, v192
	s_nop 0
	v_cndmask_b32_e32 v42, v176, v42, vcc
	v_cmp_le_i32_e32 vcc, v241, v152
	v_add_u32_e32 v241, 0x73, v192
	s_nop 0
	v_cndmask_b32_e32 v59, v176, v59, vcc
	v_cmp_le_i32_e32 vcc, v241, v152
	v_add_u32_e32 v241, 0x58, v192
	s_nop 0
	v_cndmask_b32_e32 v43, v176, v43, vcc
	v_cmp_le_i32_e32 vcc, v241, v152
	v_add_u32_e32 v241, 0x78, v192
	s_nop 0
	v_cndmask_b32_e32 v60, v176, v60, vcc
	v_cmp_le_i32_e32 vcc, v241, v152
	v_add_u32_e32 v241, 0x59, v192
	s_nop 0
	v_cndmask_b32_e32 v44, v176, v44, vcc
	v_cmp_le_i32_e32 vcc, v241, v152
	v_add_u32_e32 v241, 0x79, v192
	s_nop 0
	v_cndmask_b32_e32 v61, v176, v61, vcc
	v_cmp_le_i32_e32 vcc, v241, v152
	v_add_u32_e32 v241, 0x5a, v192
	s_nop 0
	v_cndmask_b32_e32 v45, v176, v45, vcc
	v_cmp_le_i32_e32 vcc, v241, v152
	v_add_u32_e32 v241, 0x7a, v192
	s_nop 0
	v_cndmask_b32_e32 v62, v176, v62, vcc
	v_cmp_le_i32_e32 vcc, v241, v152
	v_add_u32_e32 v241, 0x5b, v192
	s_nop 0
	v_cndmask_b32_e32 v46, v176, v46, vcc
	v_cmp_le_i32_e32 vcc, v241, v152
	v_add_u32_e32 v241, 0x7b, v192
	s_nop 0
	v_cndmask_b32_e32 v63, v176, v63, vcc
	v_cmp_le_i32_e32 vcc, v241, v152
	s_nop 1
	v_cndmask_b32_e32 v47, v176, v47, vcc

.LBB0_207:
	s_waitcnt lgkmcnt(0)
	s_barrier
	s_mul_i32 s36, s79, 0xffffe100
	s_add_i32 s36, s87, s36
	v_add_u32_e32 v68, s87, v156
	v_lshl_add_u32 v76, v157, 2, s36
	v_add_u32_e32 v238, s87, v155
	v_add_u32_e32 v239, s87, v154
	v_add_u32_e32 v240, s87, v153
	ds_read_b128 v[206:209], v68 offset:24576
	ds_read_b128 v[80:83], v76 offset:51200
	ds_read_b128 v[84:87], v76 offset:51232
	ds_read_b128 v[88:91], v76 offset:51264
	ds_read_b128 v[92:95], v76 offset:51296
	ds_read_b128 v[210:213], v68 offset:28672
	ds_read_b128 v[64:67], v76 offset:51328
	ds_read_b128 v[68:71], v76 offset:51360
	ds_read_b128 v[72:75], v76 offset:51392
	ds_read_b128 v[76:79], v76 offset:51424
	ds_read_b128 v[214:217], v238 offset:24576
	ds_read_b128 v[218:221], v238 offset:28672
	ds_read_b128 v[222:225], v239 offset:24576
	ds_read_b128 v[226:229], v239 offset:28672
	ds_read_b128 v[230:233], v240 offset:24576
	s_add_i32 s81, s81, 3
	v_cndmask_b32_e64 v136, v136, v163, s[10:11]
	v_mul_f32_e32 v137, 0xbe38aa3b, v136
	v_fmamk_f32 v48, v48, 0x3e38aa3b, v137
	v_fmamk_f32 v49, v49, 0x3e38aa3b, v137
	v_fmamk_f32 v50, v50, 0x3e38aa3b, v137
	v_fmamk_f32 v51, v51, 0x3e38aa3b, v137
	v_fmamk_f32 v52, v52, 0x3e38aa3b, v137
	v_fmamk_f32 v53, v53, 0x3e38aa3b, v137
	v_fmamk_f32 v54, v54, 0x3e38aa3b, v137
	v_fmamk_f32 v55, v55, 0x3e38aa3b, v137
	v_fmamk_f32 v56, v56, 0x3e38aa3b, v137
	v_fmamk_f32 v57, v57, 0x3e38aa3b, v137
	v_fmamk_f32 v58, v58, 0x3e38aa3b, v137
	v_fmamk_f32 v59, v59, 0x3e38aa3b, v137
	s_waitcnt lgkmcnt(10)
	v_mfma_f32_32x32x16_bf16 v[80:95], v[206:209], v[96:99], v[80:95]
	v_fmamk_f32 v60, v60, 0x3e38aa3b, v137
	v_fmamk_f32 v61, v61, 0x3e38aa3b, v137
	v_fmamk_f32 v62, v62, 0x3e38aa3b, v137
	v_fmamk_f32 v63, v63, 0x3e38aa3b, v137
	v_fmamk_f32 v32, v32, 0x3e38aa3b, v137
	v_fmamk_f32 v33, v33, 0x3e38aa3b, v137
	v_fmamk_f32 v34, v34, 0x3e38aa3b, v137
	v_fmamk_f32 v35, v35, 0x3e38aa3b, v137
	v_fmamk_f32 v36, v36, 0x3e38aa3b, v137
	v_fmamk_f32 v37, v37, 0x3e38aa3b, v137
	v_fmamk_f32 v38, v38, 0x3e38aa3b, v137
	v_fmamk_f32 v39, v39, 0x3e38aa3b, v137
	v_fmamk_f32 v40, v40, 0x3e38aa3b, v137
	v_fmamk_f32 v41, v41, 0x3e38aa3b, v137
	ds_read_b128 v[234:237], v240 offset:28672
	s_waitcnt lgkmcnt(6)
	v_mfma_f32_32x32x16_bf16 v[64:79], v[210:213], v[96:99], v[64:79]
	v_fmamk_f32 v42, v42, 0x3e38aa3b, v137
	v_fmamk_f32 v43, v43, 0x3e38aa3b, v137
	v_fmamk_f32 v44, v44, 0x3e38aa3b, v137
	v_fmamk_f32 v45, v45, 0x3e38aa3b, v137
	v_fmamk_f32 v46, v46, 0x3e38aa3b, v137
	v_fmac_f32_e32 v137, 0x3e38aa3b, v47
	v_exp_f32_e32 v47, v48
	v_exp_f32_e32 v138, v49
	v_exp_f32_e32 v50, v50
	v_exp_f32_e32 v51, v51
	v_exp_f32_e32 v52, v52
	v_exp_f32_e32 v139, v32
	v_add_f32_e32 v32, 0, v47
	v_exp_f32_e32 v53, v53
	s_waitcnt lgkmcnt(5)
	v_mfma_f32_32x32x16_bf16 v[80:95], v[214:217], v[100:103], v[80:95]
	v_add_f32_e32 v32, v138, v32
	v_exp_f32_e32 v54, v54
	v_add_f32_e32 v32, v50, v32
	v_exp_f32_e32 v55, v55
	v_add_f32_e32 v32, v51, v32
	v_exp_f32_e32 v56, v56
	v_add_f32_e32 v32, v52, v32
	v_exp_f32_e32 v57, v57
	v_add_f32_e32 v32, v53, v32
	v_exp_f32_e32 v58, v58
	v_add_f32_e32 v32, v54, v32
	v_exp_f32_e32 v59, v59
	v_add_f32_e32 v32, v55, v32
	v_exp_f32_e32 v60, v60
	s_waitcnt lgkmcnt(4)
	v_mfma_f32_32x32x16_bf16 v[64:79], v[218:221], v[100:103], v[64:79]
	v_add_f32_e32 v32, v56, v32
	v_exp_f32_e32 v61, v61
	v_add_f32_e32 v32, v57, v32
	v_exp_f32_e32 v62, v62
	v_add_f32_e32 v32, v58, v32
	v_exp_f32_e32 v63, v63
	v_add_f32_e32 v32, v59, v32
	v_add_f32_e32 v32, v60, v32
	v_exp_f32_e32 v140, v33
	v_add_f32_e32 v32, v61, v32
	v_exp_f32_e32 v141, v34
	v_add_f32_e32 v32, v62, v32
	v_exp_f32_e32 v163, v35
	v_add_f32_e32 v32, v63, v32
	s_waitcnt lgkmcnt(3)
	v_mfma_f32_32x32x16_bf16 v[80:95], v[222:225], v[104:107], v[80:95]
	v_exp_f32_e32 v169, v36
	v_add_f32_e32 v32, v139, v32
	v_exp_f32_e32 v170, v37
	v_add_f32_e32 v32, v140, v32
	v_exp_f32_e32 v171, v38
	v_add_f32_e32 v32, v141, v32
	v_exp_f32_e32 v172, v39
	v_add_f32_e32 v32, v163, v32
	v_exp_f32_e32 v173, v40
	v_add_f32_e32 v32, v169, v32
	v_exp_f32_e32 v178, v41
	v_add_f32_e32 v32, v170, v32
	v_exp_f32_e32 v179, v42
	v_add_f32_e32 v32, v171, v32
	s_waitcnt lgkmcnt(2)
	v_mfma_f32_32x32x16_bf16 v[64:79], v[226:229], v[104:107], v[64:79]
	v_exp_f32_e32 v180, v43
	v_add_f32_e32 v32, v172, v32
	v_exp_f32_e32 v181, v44
	v_add_f32_e32 v32, v173, v32
	v_exp_f32_e32 v182, v45
	v_add_f32_e32 v32, v178, v32
	v_exp_f32_e32 v183, v46
	v_add_f32_e32 v32, v179, v32
	v_exp_f32_e32 v137, v137
	v_add_f32_e32 v32, v180, v32
	v_add_f32_e32 v32, v181, v32
	v_add_f32_e32 v32, v182, v32
	v_add_f32_e32 v32, v183, v32
	v_add_f32_e32 v48, v137, v32
	s_waitcnt lgkmcnt(1)
	v_mfma_f32_32x32x16_bf16 v[80:95], v[230:233], v[108:111], v[80:95]
	v_mov_b32_e32 v49, v48
	v_cvt_pk_bf16_f32 v32, v47, v138
	v_cvt_pk_bf16_f32 v33, v50, v51
	v_cvt_pk_bf16_f32 v34, v52, v53
	v_cvt_pk_bf16_f32 v35, v54, v55
	v_cvt_pk_bf16_f32 v36, v56, v57
	v_cvt_pk_bf16_f32 v37, v58, v59
	v_cvt_pk_bf16_f32 v38, v60, v61
	v_cvt_pk_bf16_f32 v39, v62, v63
	v_cvt_pk_bf16_f32 v40, v139, v140
	v_cvt_pk_bf16_f32 v41, v141, v163
	v_cvt_pk_bf16_f32 v42, v169, v170
	v_cvt_pk_bf16_f32 v43, v171, v172
	v_cvt_pk_bf16_f32 v44, v173, v178
	s_waitcnt lgkmcnt(0)
	v_mfma_f32_32x32x16_bf16 v[64:79], v[234:237], v[108:111], v[64:79]
	v_cvt_pk_bf16_f32 v45, v179, v180
	v_cvt_pk_bf16_f32 v46, v181, v182
	v_cvt_pk_bf16_f32 v47, v183, v137
	s_nop 1
	v_permlane32_swap_b32_e32 v48, v49
	s_cmp_lt_i32 s81, 0
	s_cbranch_scc1 .LBB0_209
	v_add_u32_e32 v242, 0xa0, v192
	v_add_u32_e32 v241, 0x80, v192
	v_cmp_le_i32_e32 vcc, v242, v152
	s_nop 7
	v_cndmask_b32_e32 v64, v176, v64, vcc
	v_cmp_lt_i32_e32 vcc, v241, v152
	s_nop 1
	v_cndmask_b32_e32 v81, v176, v81, vcc
	v_cmp_le_i32_e32 vcc, v241, v152
	v_add_u32_e32 v241, 0xa1, v192
	s_nop 0
	v_cndmask_b32_e32 v80, v176, v80, vcc
	v_cmp_le_i32_e32 vcc, v241, v152
	v_add_u32_e32 v241, 0x82, v192
	s_nop 0
	v_cndmask_b32_e32 v65, v176, v65, vcc
	v_cmp_le_i32_e32 vcc, v241, v152
	v_add_u32_e32 v241, 0xa2, v192
	s_nop 0
	v_cndmask_b32_e32 v82, v176, v82, vcc
	v_cmp_le_i32_e32 vcc, v241, v152
	v_add_u32_e32 v241, 0x83, v192
	s_nop 0
	v_cndmask_b32_e32 v66, v176, v66, vcc
	v_cmp_le_i32_e32 vcc, v241, v152
	v_add_u32_e32 v241, 0xa3, v192
	s_nop 0
	v_cndmask_b32_e32 v83, v176, v83, vcc
	v_cmp_le_i32_e32 vcc, v241, v152
	v_add_u32_e32 v241, 0x88, v192
	s_nop 0
	v_cndmask_b32_e32 v67, v176, v67, vcc
	v_cmp_le_i32_e32 vcc, v241, v152
	v_add_u32_e32 v241, 0xa8, v192
	s_nop 0
	v_cndmask_b32_e32 v84, v176, v84, vcc
	v_cmp_le_i32_e32 vcc, v241, v152
	v_add_u32_e32 v241, 0x89, v192
	s_nop 0
	v_cndmask_b32_e32 v68, v176, v68, vcc
	v_cmp_le_i32_e32 vcc, v241, v152
	v_add_u32_e32 v241, 0xa9, v192
	s_nop 0
	v_cndmask_b32_e32 v85, v176, v85, vcc
	v_cmp_le_i32_e32 vcc, v241, v152
	v_add_u32_e32 v241, 0x8a, v192
	s_nop 0
	v_cndmask_b32_e32 v69, v176, v69, vcc
	v_cmp_le_i32_e32 vcc, v241, v152
	v_add_u32_e32 v241, 0xaa, v192
	s_nop 0
	v_cndmask_b32_e32 v86, v176, v86, vcc
	v_cmp_le_i32_e32 vcc, v241, v152
	v_add_u32_e32 v241, 0x8b, v192
	s_nop 0
	v_cndmask_b32_e32 v70, v176, v70, vcc
	v_cmp_le_i32_e32 vcc, v241, v152
	v_add_u32_e32 v241, 0xab, v192
	s_nop 0
	v_cndmask_b32_e32 v87, v176, v87, vcc
	v_cmp_le_i32_e32 vcc, v241, v152
	v_add_u32_e32 v241, 0x90, v192
	s_nop 0
	v_cndmask_b32_e32 v71, v176, v71, vcc
	v_cmp_le_i32_e32 vcc, v241, v152
	v_add_u32_e32 v241, 0xb0, v192
	s_nop 0
	v_cndmask_b32_e32 v88, v176, v88, vcc
	v_cmp_le_i32_e32 vcc, v241, v152
	v_add_u32_e32 v241, 0x91, v192
	s_nop 0
	v_cndmask_b32_e32 v72, v176, v72, vcc
	v_cmp_le_i32_e32 vcc, v241, v152
	v_add_u32_e32 v241, 0xb1, v192
	s_nop 0
	v_cndmask_b32_e32 v89, v176, v89, vcc
	v_cmp_le_i32_e32 vcc, v241, v152
	v_add_u32_e32 v241, 0x92, v192
	s_nop 0
	v_cndmask_b32_e32 v73, v176, v73, vcc
	v_cmp_le_i32_e32 vcc, v241, v152
	v_add_u32_e32 v241, 0xb2, v192
	s_nop 0
	v_cndmask_b32_e32 v90, v176, v90, vcc
	v_cmp_le_i32_e32 vcc, v241, v152
	v_add_u32_e32 v241, 0x93, v192
	s_nop 0
	v_cndmask_b32_e32 v74, v176, v74, vcc
	v_cmp_le_i32_e32 vcc, v241, v152
	v_add_u32_e32 v241, 0xb3, v192
	s_nop 0
	v_cndmask_b32_e32 v91, v176, v91, vcc
	v_cmp_le_i32_e32 vcc, v241, v152
	v_add_u32_e32 v241, 0x98, v192
	s_nop 0
	v_cndmask_b32_e32 v75, v176, v75, vcc
	v_cmp_le_i32_e32 vcc, v241, v152
	v_add_u32_e32 v241, 0xb8, v192
	s_nop 0
	v_cndmask_b32_e32 v92, v176, v92, vcc
	v_cmp_le_i32_e32 vcc, v241, v152
	v_add_u32_e32 v241, 0x99, v192
	s_nop 0
	v_cndmask_b32_e32 v76, v176, v76, vcc
	v_cmp_le_i32_e32 vcc, v241, v152
	v_add_u32_e32 v241, 0xb9, v192
	s_nop 0
	v_cndmask_b32_e32 v93, v176, v93, vcc
	v_cmp_le_i32_e32 vcc, v241, v152
	v_add_u32_e32 v241, 0x9a, v192
	s_nop 0
	v_cndmask_b32_e32 v77, v176, v77, vcc
	v_cmp_le_i32_e32 vcc, v241, v152
	v_add_u32_e32 v241, 0xba, v192
	s_nop 0
	v_cndmask_b32_e32 v94, v176, v94, vcc
	v_cmp_le_i32_e32 vcc, v241, v152
	v_add_u32_e32 v241, 0x9b, v192
	s_nop 0
	v_cndmask_b32_e32 v78, v176, v78, vcc
	v_cmp_le_i32_e32 vcc, v241, v152
	v_add_u32_e32 v241, 0xbb, v192
	s_nop 0
	v_cndmask_b32_e32 v95, v176, v95, vcc
	v_cmp_le_i32_e32 vcc, v241, v152
	s_nop 1
	v_cndmask_b32_e32 v79, v176, v79, vcc

.LBB0_223:
	s_waitcnt vmcnt(3)
	v_lshlrev_b64 v[116:117], 10, v[132:133]
	v_or_b32_e32 v116, s34, v116
	v_lshl_add_u64 v[32:33], v[116:117], 1, s[14:15]
	v_lshlrev_b32_e32 v118, 1, v148
	v_mov_b32_e32 v119, v129
	v_lshl_add_u64 v[32:33], v[32:33], 0, v[118:119]
	v_lshlrev_b32_e32 v128, 13, v146
	v_lshl_add_u64 v[34:35], v[32:33], 0, v[128:129]
	v_or_b32_e32 v114, 0x1000, v128
	v_mov_b32_e32 v115, v129
	global_load_ushort v200, v[34:35], off nt
	global_load_ushort v199, v[34:35], off offset:64 nt
	global_load_ushort v198, v[34:35], off offset:2048 nt
	global_load_ushort v197, v[34:35], off offset:2112 nt
	v_lshl_add_u64 v[34:35], v[32:33], 0, v[114:115]
	v_or_b32_e32 v112, 0x1800, v128
	v_mov_b32_e32 v113, v129
	global_load_ushort v196, v[34:35], off nt
	global_load_ushort v194, v[34:35], off offset:64 nt
	v_lshl_add_u64 v[34:35], v[32:33], 0, v[112:113]
	v_or_b32_e32 v92, 0x4000, v128
	v_mov_b32_e32 v93, v129
	global_load_ushort v195, v[34:35], off nt
	global_load_ushort v193, v[34:35], off offset:64 nt
	v_lshl_add_u64 v[34:35], v[32:33], 0, v[92:93]
	v_or_b32_e32 v84, 0x4800, v128
	v_mov_b32_e32 v85, v129
	global_load_ushort v192, v[34:35], off nt
	global_load_ushort v191, v[34:35], off offset:64 nt
	v_lshl_add_u64 v[34:35], v[32:33], 0, v[84:85]
	v_or_b32_e32 v82, 0x5000, v128
	v_mov_b32_e32 v83, v129
	global_load_ushort v168, v[34:35], off nt
	global_load_ushort v167, v[34:35], off offset:64 nt
	v_lshl_add_u64 v[34:35], v[32:33], 0, v[82:83]
	v_or_b32_e32 v80, 0x5800, v128
	v_mov_b32_e32 v81, v129
	global_load_ushort v166, v[34:35], off nt
	global_load_ushort v164, v[34:35], off offset:64 nt
	v_lshl_add_u64 v[34:35], v[32:33], 0, v[80:81]
	v_or_b32_e32 v78, 0x8000, v128
	v_mov_b32_e32 v79, v129
	global_load_ushort v165, v[34:35], off nt
	global_load_ushort v162, v[34:35], off offset:64 nt
	v_lshl_add_u64 v[34:35], v[32:33], 0, v[78:79]
	v_or_b32_e32 v76, 0x8800, v128
	v_mov_b32_e32 v77, v129
	global_load_ushort v161, v[34:35], off nt
	global_load_ushort v160, v[34:35], off offset:64 nt
	v_lshl_add_u64 v[34:35], v[32:33], 0, v[76:77]
	v_or_b32_e32 v74, 0x9000, v128
	v_mov_b32_e32 v75, v129
	global_load_ushort v159, v[34:35], off nt
	global_load_ushort v158, v[34:35], off offset:64 nt
	v_lshl_add_u64 v[34:35], v[32:33], 0, v[74:75]
	v_or_b32_e32 v72, 0x9800, v128
	v_mov_b32_e32 v73, v129
	global_load_ushort v148, v[34:35], off nt
	global_load_ushort v133, v[34:35], off offset:64 nt
	v_lshl_add_u64 v[34:35], v[32:33], 0, v[72:73]
	v_or_b32_e32 v70, 0xc000, v128
	v_mov_b32_e32 v71, v129
	global_load_ushort v146, v[34:35], off nt
	global_load_ushort v132, v[34:35], off offset:64 nt
	v_lshl_add_u64 v[34:35], v[32:33], 0, v[70:71]
	v_or_b32_e32 v68, 0xc800, v128
	v_mov_b32_e32 v69, v129
	global_load_ushort v127, v[34:35], off nt
	global_load_ushort v126, v[34:35], off offset:64 nt
	v_lshl_add_u64 v[34:35], v[32:33], 0, v[68:69]
	v_or_b32_e32 v66, 0xd000, v128
	v_mov_b32_e32 v67, v129
	v_or_b32_e32 v64, 0xd800, v128
	v_mov_b32_e32 v65, v129
	global_load_ushort v125, v[34:35], off nt
	global_load_ushort v124, v[34:35], off offset:64 nt
	v_lshl_add_u64 v[34:35], v[32:33], 0, v[66:67]
	v_lshl_add_u64 v[32:33], v[32:33], 0, v[64:65]
	global_load_ushort v123, v[34:35], off nt
	global_load_ushort v121, v[34:35], off offset:64 nt
	global_load_ushort v122, v[32:33], off nt
	global_load_ushort v120, v[32:33], off offset:64 nt
	s_lshl_b32 s3, s2, 13
	s_mulk_i32 s2, 0xe100
	s_add_i32 s2, s3, s2
	v_or_b32_e32 v52, s3, v156
	v_lshl_or_b32 v60, v157, 2, s2
	ds_read_b128 v[48:51], v52 offset:24576
	ds_read_b128 v[32:35], v60 offset:51200
	ds_read_b128 v[36:39], v60 offset:51232
	ds_read_b128 v[40:43], v60 offset:51264
	ds_read_b128 v[44:47], v60 offset:51296
	ds_read_b128 v[202:205], v52 offset:28672
	s_waitcnt lgkmcnt(1)
	v_mfma_f32_32x32x16_bf16 v[32:47], v[48:51], v[96:99], v[32:47]
	ds_read_b128 v[48:51], v60 offset:51328
	ds_read_b128 v[52:55], v60 offset:51360
	ds_read_b128 v[56:59], v60 offset:51392
	ds_read_b128 v[60:63], v60 offset:51424
	v_or_b32_e32 v119, s3, v155
	v_exp_f32_e32 v94, v94
	v_exp_f32_e32 v95, v95
	v_exp_f32_e32 v90, v90
	v_exp_f32_e32 v91, v91
	s_waitcnt lgkmcnt(0)
	v_mfma_f32_32x32x16_bf16 v[48:63], v[202:205], v[96:99], v[48:63]
	ds_read_b128 v[96:99], v119 offset:24576
	ds_read_b128 v[202:205], v119 offset:28672
	v_or_b32_e32 v119, s3, v154
	s_waitcnt lgkmcnt(1)
	v_mfma_f32_32x32x16_bf16 v[32:47], v[96:99], v[100:103], v[32:47]
	s_waitcnt lgkmcnt(0)
	v_mfma_f32_32x32x16_bf16 v[48:63], v[202:205], v[100:103], v[48:63]
	ds_read_b128 v[96:99], v119 offset:24576
	ds_read_b128 v[100:103], v119 offset:28672
	v_or_b32_e32 v119, s3, v153
	s_waitcnt lgkmcnt(1)
	v_mfma_f32_32x32x16_bf16 v[32:47], v[96:99], v[104:107], v[32:47]
	ds_read_b128 v[96:99], v119 offset:28672
	s_waitcnt lgkmcnt(1)
	v_mfma_f32_32x32x16_bf16 v[48:63], v[100:103], v[104:107], v[48:63]
	v_or_b32_e32 v101, 0xe0, v157
	v_or_b32_e32 v100, 0xc0, v157
	v_cmp_le_i32_e32 vcc, v101, v152
	v_exp_f32_e32 v105, v138
	v_exp_f32_e32 v106, v139
	v_exp_f32_e32 v107, v136
	s_waitcnt lgkmcnt(0)
	v_mfma_f32_32x32x16_bf16 v[48:63], v[96:99], v[108:111], v[48:63]
	ds_read_b128 v[96:99], v119 offset:24576
	v_exp_f32_e32 v119, v89
	s_waitcnt lgkmcnt(0)
	v_mfma_f32_32x32x16_bf16 v[32:47], v[96:99], v[108:111], v[32:47]
	s_nop 7
	v_cndmask_b32_e32 v48, v176, v48, vcc
	v_cmp_le_i32_e32 vcc, v100, v152
	v_exp_f32_e32 v99, v141
	v_exp_f32_e32 v108, v137
	v_exp_f32_e32 v109, v134
	v_exp_f32_e32 v110, v135
	v_exp_f32_e32 v111, v88
	v_cndmask_b32_e32 v96, v176, v32, vcc
	v_cmp_lt_i32_e32 vcc, v100, v152
	v_or_b32_e32 v32, 0xe1, v157
	v_exp_f32_e32 v134, v86
	v_cndmask_b32_e32 v97, v176, v33, vcc
	v_cmp_le_i32_e32 vcc, v32, v152
	v_or_b32_e32 v32, 0xc2, v157
	v_exp_f32_e32 v135, v87
	v_cndmask_b32_e32 v49, v176, v49, vcc
	v_cmp_le_i32_e32 vcc, v32, v152
	v_or_b32_e32 v32, 0xe2, v157
	v_cvt_pk_bf16_f32 v86, v188, v190
	v_cvt_pk_bf16_f32 v87, v186, v189
	v_cvt_pk_bf16_f32 v88, v184, v187
	v_cvt_pk_bf16_f32 v89, v183, v185
	s_nop 0
	v_cndmask_b32_e32 v98, v176, v34, vcc
	v_cmp_le_i32_e32 vcc, v32, v152
	v_or_b32_e32 v32, 0xc3, v157
	v_cndmask_b32_e32 v34, v176, v50, vcc
	v_cmp_le_i32_e32 vcc, v32, v152
	v_or_b32_e32 v32, 0xe3, v157
	v_cvt_pk_bf16_f32 v100, v171, v180
	v_cvt_pk_bf16_f32 v101, v170, v172
	v_cvt_pk_bf16_f32 v102, v169, v182
	v_cvt_pk_bf16_f32 v103, v173, v181
	s_nop 0
	v_cndmask_b32_e32 v50, v176, v35, vcc
	v_cmp_le_i32_e32 vcc, v32, v152
	v_or_b32_e32 v32, 0xc8, v157
	v_cndmask_b32_e32 v35, v176, v51, vcc
	v_cmp_le_i32_e32 vcc, v32, v152
	v_or_b32_e32 v32, 0xe8, v157
	v_cndmask_b32_e32 v51, v176, v36, vcc
	v_cmp_le_i32_e32 vcc, v32, v152
	v_or_b32_e32 v32, 0xc9, v157
	v_cndmask_b32_e32 v36, v176, v52, vcc
	v_cmp_le_i32_e32 vcc, v32, v152
	v_or_b32_e32 v32, 0xe9, v157
	s_nop 0
	v_cndmask_b32_e32 v52, v176, v37, vcc
	v_cmp_le_i32_e32 vcc, v32, v152
	v_or_b32_e32 v32, 0xca, v157
	s_nop 0
	v_cndmask_b32_e32 v37, v176, v53, vcc
	v_cmp_le_i32_e32 vcc, v32, v152
	v_or_b32_e32 v32, 0xea, v157
	s_nop 0
	v_cndmask_b32_e32 v53, v176, v38, vcc
	v_cmp_le_i32_e32 vcc, v32, v152
	v_or_b32_e32 v32, 0xcb, v157
	s_nop 0
	v_cndmask_b32_e32 v38, v176, v54, vcc
	v_cmp_le_i32_e32 vcc, v32, v152
	v_or_b32_e32 v32, 0xeb, v157
	s_nop 0
	v_cndmask_b32_e32 v54, v176, v39, vcc
	v_cmp_le_i32_e32 vcc, v32, v152
	v_or_b32_e32 v32, 0xd0, v157
	s_nop 0
	v_cndmask_b32_e32 v39, v176, v55, vcc
	v_cmp_le_i32_e32 vcc, v32, v152
	v_or_b32_e32 v32, 0xf0, v157
	s_nop 0
	v_cndmask_b32_e32 v55, v176, v40, vcc
	v_cmp_le_i32_e32 vcc, v32, v152
	v_or_b32_e32 v32, 0xd1, v157
	s_nop 0
	v_cndmask_b32_e32 v40, v176, v56, vcc
	v_cmp_le_i32_e32 vcc, v32, v152
	v_or_b32_e32 v32, 0xf1, v157
	s_nop 0
	v_cndmask_b32_e32 v56, v176, v41, vcc
	v_cmp_le_i32_e32 vcc, v32, v152
	v_or_b32_e32 v32, 0xd2, v157
	s_nop 0
	v_cndmask_b32_e32 v41, v176, v57, vcc
	v_cmp_le_i32_e32 vcc, v32, v152
	v_or_b32_e32 v32, 0xf2, v157
	s_nop 0
	v_cndmask_b32_e32 v57, v176, v42, vcc
	v_cmp_le_i32_e32 vcc, v32, v152
	v_or_b32_e32 v32, 0xd3, v157
	s_nop 0
	v_cndmask_b32_e32 v42, v176, v58, vcc
	v_cmp_le_i32_e32 vcc, v32, v152
	v_or_b32_e32 v32, 0xf3, v157
	s_nop 0
	v_cndmask_b32_e32 v58, v176, v43, vcc
	v_cmp_le_i32_e32 vcc, v32, v152
	v_or_b32_e32 v32, 0xd8, v157
	s_nop 0
	v_cndmask_b32_e32 v43, v176, v59, vcc
	v_cmp_le_i32_e32 vcc, v32, v152
	v_or_b32_e32 v32, 0xf8, v157
	s_nop 0
	v_cndmask_b32_e32 v59, v176, v44, vcc
	v_cmp_le_i32_e32 vcc, v32, v152
	v_or_b32_e32 v32, 0xd9, v157
	s_nop 0
	v_cndmask_b32_e32 v44, v176, v60, vcc
	v_cmp_le_i32_e32 vcc, v32, v152
	v_or_b32_e32 v32, 0xf9, v157
	s_nop 0
	v_cndmask_b32_e32 v60, v176, v45, vcc
	v_cmp_le_i32_e32 vcc, v32, v152
	v_or_b32_e32 v32, 0xda, v157
	s_nop 0
	v_cndmask_b32_e32 v45, v176, v61, vcc
	v_cmp_le_i32_e32 vcc, v32, v152
	v_or_b32_e32 v32, 0xfa, v157
	s_nop 0
	v_cndmask_b32_e32 v61, v176, v46, vcc
	v_cmp_le_i32_e32 vcc, v32, v152
	v_or_b32_e32 v32, 0xdb, v157
	s_nop 0
	v_cndmask_b32_e32 v46, v176, v62, vcc
	v_cmp_le_i32_e32 vcc, v32, v152
	v_or_b32_e32 v32, 0xfb, v157
	s_nop 0
	v_cndmask_b32_e32 v62, v176, v47, vcc
	v_cmp_le_i32_e32 vcc, v32, v152
	v_add_f32_e32 v32, 0, v188
	v_add_f32_e32 v32, v190, v32
	v_add_f32_e32 v32, v186, v32
	v_add_f32_e32 v32, v189, v32
	v_add_f32_e32 v32, v184, v32
	v_add_f32_e32 v32, v187, v32
	v_add_f32_e32 v32, v183, v32
	v_add_f32_e32 v32, v185, v32
	v_add_f32_e32 v32, v171, v32
	v_add_f32_e32 v32, v180, v32
	v_add_f32_e32 v32, v170, v32
	v_add_f32_e32 v32, v172, v32
	v_cndmask_b32_e32 v47, v176, v63, vcc
	v_exp_f32_e32 v63, v140
	v_add_f32_e32 v32, v169, v32
	v_add_f32_e32 v32, v182, v32
	v_add_f32_e32 v32, v173, v32
	v_add_f32_e32 v32, v181, v32
	v_add_f32_e32 v32, v63, v32
	v_add_f32_e32 v32, v99, v32
	v_add_f32_e32 v32, v105, v32
	v_add_f32_e32 v32, v106, v32
	v_add_f32_e32 v32, v107, v32
	v_add_f32_e32 v32, v108, v32
	v_add_f32_e32 v32, v109, v32
	v_add_f32_e32 v32, v110, v32
	v_add_f32_e32 v32, v94, v32
	v_add_f32_e32 v32, v95, v32
	v_add_f32_e32 v32, v90, v32
	v_add_f32_e32 v32, v91, v32
	v_add_f32_e32 v32, v111, v32
	v_add_f32_e32 v32, v119, v32
	v_add_f32_e32 v32, v134, v32
	v_add_f32_e32 v32, v135, v32
	v_mov_b32_e32 v33, v32
	s_nop 1
	v_permlane32_swap_b32_e32 v32, v33
	v_cvt_pk_bf16_f32 v104, v63, v99
	v_cvt_pk_bf16_f32 v105, v105, v106
	v_cvt_pk_bf16_f32 v106, v107, v108
	v_cvt_pk_bf16_f32 v107, v109, v110
	v_cvt_pk_bf16_f32 v108, v94, v95
	v_cvt_pk_bf16_f32 v109, v90, v91
	v_cvt_pk_bf16_f32 v110, v111, v119
	v_cvt_pk_bf16_f32 v111, v134, v135
	s_nop 0
	v_add_u32_e32 v63, s87, v151
	ds_read_b64_tr_b16 v[134:135],v63 offset:0
	ds_read_b64_tr_b16 v[136:137],v63 offset:128
	ds_read_b64_tr_b16 v[138:139],v63 offset:512
	ds_read_b64_tr_b16 v[140:141],v63 offset:640
	ds_read_b64_tr_b16 v[152:153],v63 offset:4096
	ds_read_b64_tr_b16 v[154:155],v63 offset:4224
	ds_read_b64_tr_b16 v[170:171],v63 offset:4608
	ds_read_b64_tr_b16 v[172:173],v63 offset:4736
	s_waitcnt lgkmcnt(0)
	s_nop 0
	v_mfma_f32_32x32x16_bf16 v[16:31], v[86:89], v[134:137], v[16:31]
	ds_read_b64_tr_b16 v[134:135],v63 offset:2048
	ds_read_b64_tr_b16 v[136:137],v63 offset:2176
	v_mfma_f32_32x32x16_bf16 v[16:31], v[100:103], v[138:141], v[16:31]
	ds_read_b64_tr_b16 v[138:139],v63 offset:2560
	ds_read_b64_tr_b16 v[140:141],v63 offset:2688
	v_mfma_f32_32x32x16_bf16 v[16:31], v[104:107], v[152:155], v[16:31]
	ds_read_b64_tr_b16 v[152:153],v63 offset:6144
	ds_read_b64_tr_b16 v[154:155],v63 offset:6272
	v_mfma_f32_32x32x16_bf16 v[16:31], v[108:111], v[170:173], v[16:31]
	ds_read_b64_tr_b16 v[170:171],v63 offset:6656
	ds_read_b64_tr_b16 v[172:173],v63 offset:6784
	s_waitcnt lgkmcnt(0)
	v_mfma_f32_32x32x16_bf16 v[0:15], v[86:89], v[134:137], v[0:15]
	v_max_f32_e32 v63, v97, v97
	v_max_f32_e32 v86, v96, v96
	v_max_f32_e32 v63, v86, v63
	v_max3_f32 v63, v63, v98, v50
	v_max3_f32 v63, v63, v51, v52
	v_max3_f32 v63, v63, v53, v54
	v_max3_f32 v63, v63, v55, v56
	v_mfma_f32_32x32x16_bf16 v[0:15], v[100:103], v[138:141], v[0:15]
	v_max3_f32 v63, v63, v57, v58
	v_max3_f32 v63, v63, v59, v60
	v_max3_f32 v63, v63, v61, v62
	v_max3_f32 v63, v63, v48, v49
	v_max3_f32 v63, v63, v34, v35
	v_max3_f32 v63, v63, v36, v37
	v_max3_f32 v63, v63, v38, v39
	v_mfma_f32_32x32x16_bf16 v[0:15], v[104:107], v[152:155], v[0:15]
	v_max3_f32 v63, v63, v40, v41
	v_max3_f32 v63, v63, v42, v43
	v_max3_f32 v63, v63, v44, v45
	v_max3_f32 v63, v63, v46, v47
	v_mov_b32_e32 v86, v63
	s_nop 1
	v_permlane32_swap_b32_e32 v63, v86
	v_mfma_f32_32x32x16_bf16 v[0:15], v[108:111], v[170:173], v[0:15]
	v_max_f32_e32 v86, v86, v86
	v_max_f32_e32 v63, v63, v63
	v_max_f32_e32 v86, v63, v86
	v_sub_f32_e32 v63, v86, v163
	v_mul_f32_e32 v63, 0x3e000000, v63
	s_mov_b32 s2, 0x41800000
	v_cmp_ge_f32_e32 vcc, s2, v63
	v_mov_b32_e32 v63, 1.0
	s_cmp_lg_u64 vcc, exec
	s_cbranch_scc1 .LBB0_294

.LBB0_228:
	v_mul_f32_e32 v86, 0xbe38aa3b, v163
	v_fmamk_f32 v87, v96, 0x3e38aa3b, v86
	v_fmamk_f32 v88, v97, 0x3e38aa3b, v86
	v_fmamk_f32 v89, v98, 0x3e38aa3b, v86
	v_fmamk_f32 v50, v50, 0x3e38aa3b, v86
	v_fmamk_f32 v51, v51, 0x3e38aa3b, v86
	v_fmamk_f32 v52, v52, 0x3e38aa3b, v86
	v_fmamk_f32 v53, v53, 0x3e38aa3b, v86
	v_fmamk_f32 v54, v54, 0x3e38aa3b, v86
	v_fmamk_f32 v55, v55, 0x3e38aa3b, v86
	v_fmamk_f32 v56, v56, 0x3e38aa3b, v86
	v_fmamk_f32 v57, v57, 0x3e38aa3b, v86
	v_fmamk_f32 v58, v58, 0x3e38aa3b, v86
	v_fmamk_f32 v59, v59, 0x3e38aa3b, v86
	v_fmamk_f32 v60, v60, 0x3e38aa3b, v86
	v_fmamk_f32 v61, v61, 0x3e38aa3b, v86
	v_fmamk_f32 v62, v62, 0x3e38aa3b, v86
	v_fmamk_f32 v48, v48, 0x3e38aa3b, v86
	v_fmamk_f32 v49, v49, 0x3e38aa3b, v86
	v_fmamk_f32 v34, v34, 0x3e38aa3b, v86
	v_fmamk_f32 v35, v35, 0x3e38aa3b, v86
	v_fmamk_f32 v36, v36, 0x3e38aa3b, v86
	v_fmamk_f32 v37, v37, 0x3e38aa3b, v86
	v_fmamk_f32 v38, v38, 0x3e38aa3b, v86
	v_fmamk_f32 v39, v39, 0x3e38aa3b, v86
	v_fmamk_f32 v40, v40, 0x3e38aa3b, v86
	v_fmamk_f32 v41, v41, 0x3e38aa3b, v86
	v_fmamk_f32 v42, v42, 0x3e38aa3b, v86
	v_fmamk_f32 v43, v43, 0x3e38aa3b, v86
	v_fmamk_f32 v44, v44, 0x3e38aa3b, v86
	v_fmamk_f32 v45, v45, 0x3e38aa3b, v86
	v_fmamk_f32 v46, v46, 0x3e38aa3b, v86
	v_fmac_f32_e32 v86, 0x3e38aa3b, v47
	v_exp_f32_e32 v47, v87
	v_exp_f32_e32 v87, v88
	v_exp_f32_e32 v88, v89
	v_exp_f32_e32 v50, v50
	v_exp_f32_e32 v51, v51
	v_exp_f32_e32 v89, v34
	v_add_f32_e32 v34, 0, v47
	v_exp_f32_e32 v52, v52
	v_add_f32_e32 v34, v87, v34
	v_exp_f32_e32 v53, v53
	v_add_f32_e32 v34, v88, v34
	v_exp_f32_e32 v54, v54
	v_add_f32_e32 v34, v50, v34
	v_exp_f32_e32 v55, v55
	v_add_f32_e32 v34, v51, v34
	v_exp_f32_e32 v56, v56
	v_add_f32_e32 v34, v52, v34
	v_exp_f32_e32 v57, v57
	v_add_f32_e32 v34, v53, v34
	v_exp_f32_e32 v58, v58
	v_add_f32_e32 v34, v54, v34
	v_exp_f32_e32 v59, v59
	v_add_f32_e32 v34, v55, v34
	v_exp_f32_e32 v60, v60
	v_add_f32_e32 v34, v56, v34
	v_exp_f32_e32 v61, v61
	v_add_f32_e32 v34, v57, v34
	v_exp_f32_e32 v62, v62
	v_add_f32_e32 v34, v58, v34
	v_exp_f32_e32 v48, v48
	v_add_f32_e32 v34, v59, v34
	v_exp_f32_e32 v49, v49
	v_add_f32_e32 v34, v60, v34
	v_add_f32_e32 v34, v61, v34
	v_exp_f32_e32 v90, v35
	v_add_f32_e32 v34, v62, v34
	v_exp_f32_e32 v91, v36
	v_add_f32_e32 v34, v48, v34
	v_exp_f32_e32 v94, v37
	v_add_f32_e32 v34, v49, v34
	v_exp_f32_e32 v95, v38
	v_add_f32_e32 v34, v89, v34
	v_exp_f32_e32 v96, v39
	v_add_f32_e32 v34, v90, v34
	v_exp_f32_e32 v97, v40
	v_add_f32_e32 v34, v91, v34
	v_exp_f32_e32 v98, v41
	v_add_f32_e32 v34, v94, v34
	v_exp_f32_e32 v99, v42
	v_add_f32_e32 v34, v95, v34
	v_exp_f32_e32 v100, v43
	v_add_f32_e32 v34, v96, v34
	v_exp_f32_e32 v101, v44
	v_add_f32_e32 v34, v97, v34
	v_exp_f32_e32 v102, v45
	v_add_f32_e32 v34, v98, v34
	v_exp_f32_e32 v103, v46
	v_add_f32_e32 v34, v99, v34
	v_exp_f32_e32 v86, v86
	v_add_f32_e32 v34, v100, v34
	v_add_f32_e32 v34, v101, v34
	v_add_f32_e32 v34, v102, v34
	v_add_f32_e32 v34, v103, v34
	v_add_f32_e32 v34, v86, v34
	v_mov_b32_e32 v35, v34
	s_nop 1
	v_permlane32_swap_b32_e32 v34, v35
	v_cvt_pk_bf16_f32 v36, v47, v87
	v_cvt_pk_bf16_f32 v37, v88, v50
	v_cvt_pk_bf16_f32 v38, v51, v52
	v_cvt_pk_bf16_f32 v39, v53, v54
	v_cvt_pk_bf16_f32 v40, v55, v56
	v_cvt_pk_bf16_f32 v41, v57, v58
	v_cvt_pk_bf16_f32 v42, v59, v60
	v_cvt_pk_bf16_f32 v43, v61, v62
	v_cvt_pk_bf16_f32 v44, v48, v49
	v_cvt_pk_bf16_f32 v45, v89, v90
	v_cvt_pk_bf16_f32 v46, v91, v94
	v_cvt_pk_bf16_f32 v47, v95, v96
	v_cvt_pk_bf16_f32 v48, v97, v98
	v_cvt_pk_bf16_f32 v49, v99, v100
	v_cvt_pk_bf16_f32 v50, v101, v102
	v_cvt_pk_bf16_f32 v51, v103, v86
	s_nop 0
	v_add_u32_e32 v60, s3, v151
	ds_read_b64_tr_b16 v[52:53],v60 offset:0
	ds_read_b64_tr_b16 v[54:55],v60 offset:128
	ds_read_b64_tr_b16 v[56:57],v60 offset:512
	ds_read_b64_tr_b16 v[58:59],v60 offset:640
	ds_read_b64_tr_b16 v[86:87],v60 offset:4096
	ds_read_b64_tr_b16 v[88:89],v60 offset:4224
	ds_read_b64_tr_b16 v[94:95],v60 offset:4608
	ds_read_b64_tr_b16 v[96:97],v60 offset:4736
	s_waitcnt lgkmcnt(0)
	s_nop 0
	v_mfma_f32_32x32x16_bf16 v[16:31], v[36:39], v[52:55], v[16:31]
	ds_read_b64_tr_b16 v[52:53],v60 offset:2048
	ds_read_b64_tr_b16 v[54:55],v60 offset:2176
	v_mfma_f32_32x32x16_bf16 v[16:31], v[40:43], v[56:59], v[16:31]
	ds_read_b64_tr_b16 v[56:57],v60 offset:2560
	ds_read_b64_tr_b16 v[58:59],v60 offset:2688
	v_mfma_f32_32x32x16_bf16 v[16:31], v[44:47], v[86:89], v[16:31]
	ds_read_b64_tr_b16 v[86:87],v60 offset:6144
	ds_read_b64_tr_b16 v[88:89],v60 offset:6272
	v_mfma_f32_32x32x16_bf16 v[16:31], v[48:51], v[94:97], v[16:31]
	ds_read_b64_tr_b16 v[94:95],v60 offset:6656
	ds_read_b64_tr_b16 v[96:97],v60 offset:6784
	s_waitcnt lgkmcnt(0)
	v_mfma_f32_32x32x16_bf16 v[0:15], v[36:39], v[52:55], v[0:15]
	v_mfma_f32_32x32x16_bf16 v[0:15], v[40:43], v[56:59], v[0:15]
	v_mfma_f32_32x32x16_bf16 v[0:15], v[44:47], v[86:89], v[0:15]
	v_mfma_f32_32x32x16_bf16 v[0:15], v[48:51], v[94:97], v[0:15]
	s_setprio 0
	v_cmp_gt_u32_e32 vcc, 32, v144
	s_and_saveexec_b64 s[6:7], vcc
	v_add_f32_e32 v32, v32, v33
	v_fmac_f32_e32 v32, v150, v149
	v_add_f32_e32 v33, v34, v35
	v_fmac_f32_e32 v33, v32, v63
	ds_write_b32 v147, v33 offset:49152
	s_or_b64 exec, exec, s[6:7]
	s_waitcnt lgkmcnt(0)
	ds_read_b128 v[44:47], v145 offset:49152
	ds_read_b128 v[40:43], v145 offset:49184
	ds_read_b128 v[36:39], v145 offset:49216
	ds_read_b128 v[32:35], v145 offset:49248
	v_and_b32_e32 v48, 1, v143
	v_cmp_eq_u32_e32 vcc, 0, v48
	v_lshl_add_u64 v[48:49], v[116:117], 1, s[16:17]
	s_waitcnt lgkmcnt(3)
	v_rcp_f32_e32 v44, v44
	v_mov_b32_e32 v119, v129
	s_waitcnt vmcnt(31)
	v_lshlrev_b32_e32 v52, 16, v200
	v_lshl_add_u64 v[48:49], v[48:49], 0, v[118:119]
	v_mul_f32_e32 v16, v16, v44
	v_mul_f32_e32 v16, v16, v52
	v_mov_b32_e32 v52, 0
	v_lshl_add_u64 v[50:51], v[48:49], 0, v[128:129]
	s_nop 0
	v_mov_b32_dpp v52, v16 quad_perm:[1,0,3,2] row_mask:0xf bank_mask:0xf
	s_and_saveexec_b64 s[6:7], vcc
	s_cbranch_execz .LBB0_232
	v_cvt_pk_bf16_f32 v16, v16, v52
	global_store_dword v[50:51], v16, off
